# v24 + P6 EpiKVQ rope-table loads software-pipelined one row group ahead (double buffer v218-249)
# speedup vs baseline: 1.0193x; 1.0193x over previous
.LBB0_646:
	v_lshl_add_u32 v170, s12, 8, v188
	v_mov_b32_e32 v196, v170
	v_or_b32_e32 v168, 16, v170
	v_or_b32_e32 v166, 32, v170
	v_or_b32_e32 v164, 48, v170
	v_ashrrev_i32_e32 v171, 31, v170
	v_ashrrev_i32_e32 v169, 31, v168
	v_ashrrev_i32_e32 v167, 31, v166
	v_ashrrev_i32_e32 v165, 31, v164
	v_lshlrev_b64 v[128:129], 6, v[170:171]
	v_lshlrev_b64 v[130:131], 6, v[168:169]
	v_lshlrev_b64 v[156:157], 6, v[166:167]
	v_lshlrev_b64 v[158:159], 6, v[164:165]
	v_add_u32_e32 v162, 0x80, v170
	v_add_u32_e32 v160, 0x90, v170
	v_lshl_add_u64 v[128:129], v[146:147], 0, v[128:129]
	v_lshl_add_u64 v[132:133], v[146:147], 0, v[130:131]
	v_lshl_add_u64 v[156:157], v[146:147], 0, v[156:157]
	v_lshl_add_u64 v[158:159], v[146:147], 0, v[158:159]
	v_ashrrev_i32_e32 v163, 31, v162
	v_ashrrev_i32_e32 v161, 31, v160
	global_load_dwordx4 v[128:131], v[128:129], off
	s_nop 0
	global_load_dwordx4 v[132:135], v[132:133], off
	s_nop 0
	global_load_dwordx4 v[172:175], v[156:157], off
	global_load_dwordx4 v[176:179], v[158:159], off
	v_lshlrev_b64 v[156:157], 6, v[162:163]
	v_lshlrev_b64 v[158:159], 6, v[160:161]
	v_lshl_add_u64 v[156:157], v[146:147], 0, v[156:157]
	v_lshl_add_u64 v[158:159], v[146:147], 0, v[158:159]
	global_load_dwordx4 v[180:183], v[156:157], off
	global_load_dwordx4 v[184:187], v[158:159], off
	v_add_u32_e32 v158, 0xa0, v170
	v_ashrrev_i32_e32 v159, 31, v158
	v_lshlrev_b64 v[156:157], 6, v[158:159]
	v_lshl_add_u64 v[156:157], v[146:147], 0, v[156:157]
	global_load_dwordx4 v[204:207], v[156:157], off
	v_add_u32_e32 v156, 0xb0, v170
	v_ashrrev_i32_e32 v157, 31, v156
	v_lshlrev_b64 v[198:199], 6, v[156:157]
	v_lshl_add_u64 v[198:199], v[146:147], 0, v[198:199]
	global_load_dwordx4 v[208:211], v[198:199], off
	v_and_b32_e32 v198, 64, v194
	v_xor_b32_e32 v144, 16, v194
	v_add_u32_e32 v198, 64, v198
	v_cmp_lt_i32_e32 vcc, v144, v198
	v_xor_b32_e32 v199, 32, v194
	s_ashr_i32 s4, s16, 2
	v_cndmask_b32_e32 v144, v194, v144, vcc
	v_cmp_lt_i32_e32 vcc, v199, v198
	v_lshlrev_b32_e32 v198, 2, v144
	s_cmp_lg_u32 s4, 1
	v_cndmask_b32_e32 v199, v194, v199, vcc
	v_lshlrev_b32_e32 v200, 2, v199
	s_cselect_b64 s[12:13], -1, 0
	s_and_b64 s[22:23], s[36:37], s[12:13]
	s_and_b64 s[46:47], s[22:23], s[6:7]
	v_mov_b32_e32 v226, 1.0
	v_mov_b32_e32 v227, 1.0
	v_mov_b32_e32 v228, 1.0
	v_mov_b32_e32 v229, 1.0
	v_mov_b32_e32 v230, 1.0
	v_mov_b32_e32 v231, 1.0
	v_mov_b32_e32 v232, 1.0
	v_mov_b32_e32 v233, 1.0
	s_and_saveexec_b64 s[32:33], s[46:47]
	v_lshlrev_b32_e32 v250, 6, v196
	v_and_b32_e32 v250, 0x7ffc0, v250
	global_load_dwordx4 v[218:221], v250, s[28:29] offset:32
	global_load_dwordx4 v[222:225], v250, s[28:29] offset:48
	global_load_dwordx4 v[226:229], v250, s[28:29]
	global_load_dwordx4 v[230:233], v250, s[28:29] offset:16
	s_mov_b64 exec, s[32:33]
	s_waitcnt vmcnt(4)
	v_add_f32_e32 v128, v128, v129
	v_add_f32_e32 v129, v130, v131
	v_add_f32_e32 v128, v128, v129
	v_add_f32_e32 v129, v132, v133
	v_add_f32_e32 v130, v134, v135
	v_add_f32_e32 v131, v172, v173
	v_add_f32_e32 v132, v174, v175
	v_add_f32_e32 v133, v176, v177
	v_add_f32_e32 v134, v178, v179
	v_add_f32_e32 v135, v180, v181
	v_add_f32_e32 v144, v182, v183
	v_add_f32_e32 v172, v184, v185
	v_add_f32_e32 v173, v186, v187
	v_add_f32_e32 v174, v204, v205
	v_add_f32_e32 v175, v206, v207
	v_add_f32_e32 v129, v129, v130
	v_add_f32_e32 v130, v131, v132
	v_add_f32_e32 v176, v208, v209
	v_add_f32_e32 v177, v210, v211
	v_add_f32_e32 v131, v133, v134
	v_add_f32_e32 v132, v135, v144
	v_add_f32_e32 v133, v172, v173
	v_add_f32_e32 v134, v174, v175
	v_add_f32_e32 v135, v176, v177
	ds_bpermute_b32 v178, v198, v128
	ds_bpermute_b32 v172, v198, v129
	ds_bpermute_b32 v173, v198, v130
	ds_bpermute_b32 v174, v198, v131
	ds_bpermute_b32 v175, v198, v132
	ds_bpermute_b32 v176, v198, v133
	ds_bpermute_b32 v177, v198, v134
	ds_bpermute_b32 v179, v198, v135
	s_waitcnt lgkmcnt(7)
	v_add_f32_e32 v144, v128, v178
	s_waitcnt lgkmcnt(6)
	v_add_f32_e32 v213, v129, v172
	s_waitcnt lgkmcnt(5)
	v_add_f32_e32 v211, v130, v173
	s_waitcnt lgkmcnt(4)
	v_add_f32_e32 v209, v131, v174
	s_waitcnt lgkmcnt(3)
	v_add_f32_e32 v207, v132, v175
	s_waitcnt lgkmcnt(2)
	v_add_f32_e32 v205, v133, v176
	s_waitcnt lgkmcnt(1)
	v_add_f32_e32 v201, v134, v177
	s_waitcnt lgkmcnt(0)
	v_add_f32_e32 v199, v135, v179
	ds_bpermute_b32 v180, v200, v144
	ds_bpermute_b32 v214, v200, v213
	ds_bpermute_b32 v212, v200, v211
	ds_bpermute_b32 v210, v200, v209
	ds_bpermute_b32 v208, v200, v207
	ds_bpermute_b32 v206, v200, v205
	ds_bpermute_b32 v204, v200, v201
	ds_bpermute_b32 v200, v200, v199
	v_mov_b32_e32 v176, 0
	v_mov_b32_e32 v177, 0
	v_mov_b32_e32 v178, 0
	v_mov_b32_e32 v179, 0
	v_mov_b32_e32 v174, 0
	v_mov_b32_e32 v175, 0
	v_mov_b32_e32 v172, 0
	v_mov_b32_e32 v173, 0
	v_mov_b32_e32 v242, 1.0
	v_mov_b32_e32 v243, 1.0
	v_mov_b32_e32 v244, 1.0
	v_mov_b32_e32 v245, 1.0
	v_mov_b32_e32 v246, 1.0
	v_mov_b32_e32 v247, 1.0
	v_mov_b32_e32 v248, 1.0
	v_mov_b32_e32 v249, 1.0
	s_and_saveexec_b64 s[12:13], s[46:47]
	s_cbranch_execz .LBB0_648
	v_add_u32_e32 v250, 0x10, v196
	v_lshlrev_b32_e32 v250, 6, v250
	v_and_b32_e32 v250, 0x7ffc0, v250
	global_load_dwordx4 v[234:237], v250, s[28:29] offset:32
	global_load_dwordx4 v[238:241], v250, s[28:29] offset:48
	global_load_dwordx4 v[242:245], v250, s[28:29]
	global_load_dwordx4 v[246:249], v250, s[28:29] offset:16
	s_waitcnt vmcnt(7)
	v_xor_b32_e32 v179, 0x80000000, v221
	v_xor_b32_e32 v178, 0x80000000, v220
	v_xor_b32_e32 v177, 0x80000000, v219
	v_xor_b32_e32 v176, 0x80000000, v218
	s_waitcnt vmcnt(6)
	v_xor_b32_e32 v181, 0x80000000, v225
	v_xor_b32_e32 v186, 0x80000000, v224
	v_xor_b32_e32 v187, 0x80000000, v223
	v_xor_b32_e32 v215, 0x80000000, v222
	v_cndmask_b32_e64 v176, v218, v176, s[8:9]
	v_cndmask_b32_e64 v177, v219, v177, s[8:9]
	v_cndmask_b32_e64 v178, v220, v178, s[8:9]
	v_cndmask_b32_e64 v179, v221, v179, s[8:9]
	v_cndmask_b32_e64 v174, v222, v215, s[8:9]
	v_cndmask_b32_e64 v175, v223, v187, s[8:9]
	v_cndmask_b32_e64 v172, v224, v186, s[8:9]
	v_cndmask_b32_e64 v173, v225, v181, s[8:9]
.LBB0_648:
	s_or_b64 exec, exec, s[12:13]
	s_waitcnt lgkmcnt(7)
	v_add_f32_e32 v144, v144, v180
	v_fmamk_f32 v144, v144, 0x3a800000, v195
	v_rsq_f32_e32 v180, v144
	s_nop 0
	v_pk_mul_f32 v[184:185], v[122:123], v[180:181] op_sel_hi:[1,0]
	v_cndmask_b32_e64 v122, 0, 1, s[22:23]
	v_pk_mul_f32 v[126:127], v[126:127], v[180:181] op_sel_hi:[1,0]
	v_pk_mul_f32 v[182:183], v[124:125], v[180:181] op_sel_hi:[1,0]
	v_cmp_ne_u32_e64 s[12:13], 1, v122
	s_andn2_b64 vcc, exec, s[22:23]
	v_pk_mul_f32 v[186:187], v[120:121], v[180:181] op_sel_hi:[1,0]
	s_cbranch_vccnz .LBB0_650
	ds_bpermute_b32 v120, v198, v182
	ds_bpermute_b32 v121, v198, v183
	ds_bpermute_b32 v122, v198, v186
	ds_bpermute_b32 v124, v198, v126
	ds_bpermute_b32 v125, v198, v127
	ds_bpermute_b32 v123, v198, v187
	ds_bpermute_b32 v216, v198, v184
	ds_bpermute_b32 v217, v198, v185
	s_waitcnt lgkmcnt(6)
	v_pk_mul_f32 v[120:121], v[176:177], v[120:121]
	s_waitcnt lgkmcnt(3)
	v_pk_mul_f32 v[124:125], v[178:179], v[124:125]
	s_waitcnt vmcnt(5)
	v_pk_fma_f32 v[182:183], v[182:183], v[226:227], v[120:121]
	s_waitcnt lgkmcnt(2)
	v_pk_mul_f32 v[120:121], v[174:175], v[122:123]
	s_waitcnt lgkmcnt(0)
	v_pk_mul_f32 v[122:123], v[172:173], v[216:217]
	v_pk_fma_f32 v[126:127], v[126:127], v[228:229], v[124:125]
	s_waitcnt vmcnt(4)
	v_pk_fma_f32 v[184:185], v[184:185], v[232:233], v[122:123]
	v_pk_fma_f32 v[186:187], v[186:187], v[230:231], v[120:121]
.LBB0_650:
	s_lshl_b32 s22, s16, 8
	s_ashr_i32 s5, s4, 31
	s_lshl_b64 s[16:17], s[4:5], 26
	s_and_b32 s5, s22, 0x300
	s_add_u32 s16, s54, s16
	v_or_b32_e32 v120, s5, v190
	s_addc_u32 s17, s55, s17
	v_lshlrev_b32_e32 v144, 1, v120
	s_cmp_eq_u32 s4, 2
	v_lshl_add_u64 v[122:123], s[16:17], 0, v[144:145]
	v_lshlrev_b64 v[120:121], 11, v[170:171]
	s_cselect_b64 vcc, -1, 0
	v_lshl_add_u64 v[124:125], v[122:123], 0, v[120:121]
	v_cndmask_b32_e32 v120, 1.0, v197, vcc
	v_pk_mul_f32 v[126:127], v[120:121], v[126:127] op_sel_hi:[0,1]
	v_mov_b32_e32 v181, v180
	v_pk_mul_f32 v[170:171], v[120:121], v[182:183] op_sel_hi:[0,1]
	v_cvt_pk_bf16_f32 v182, v170, v171
	v_cvt_pk_bf16_f32 v183, v126, v127
	v_mov_b32_e32 v126, v180
	v_mov_b32_e32 v127, v180
	v_pk_mul_f32 v[216:217], v[120:121], v[184:185] op_sel_hi:[0,1]
	v_pk_mul_f32 v[184:185], v[120:121], v[186:187] op_sel_hi:[0,1]
	v_pk_mul_f32 v[118:119], v[118:119], v[126:127]
	v_pk_mul_f32 v[116:117], v[116:117], v[180:181]
	v_pk_mul_f32 v[114:115], v[114:115], v[126:127]
	s_and_b64 vcc, exec, s[12:13]
	v_pk_mul_f32 v[112:113], v[112:113], v[180:181]
	v_cvt_pk_bf16_f32 v184, v184, v185
	v_cvt_pk_bf16_f32 v185, v216, v217
	global_store_dwordx4 v[124:125], v[182:185], off
	s_cbranch_vccnz .LBB0_652
	ds_bpermute_b32 v126, v198, v116
	ds_bpermute_b32 v127, v198, v117
	ds_bpermute_b32 v170, v198, v112
	ds_bpermute_b32 v180, v198, v118
	ds_bpermute_b32 v181, v198, v119
	ds_bpermute_b32 v171, v198, v113
	ds_bpermute_b32 v182, v198, v114
	ds_bpermute_b32 v183, v198, v115
	s_waitcnt lgkmcnt(6)
	v_pk_mul_f32 v[126:127], v[176:177], v[126:127]
	s_waitcnt lgkmcnt(3)
	v_pk_mul_f32 v[176:177], v[178:179], v[180:181]
	s_waitcnt vmcnt(6)
	v_pk_fma_f32 v[116:117], v[116:117], v[226:227], v[126:127]
	s_waitcnt lgkmcnt(2)
	v_pk_mul_f32 v[126:127], v[174:175], v[170:171]
	s_waitcnt lgkmcnt(0)
	v_pk_mul_f32 v[132:133], v[172:173], v[182:183]
	v_pk_fma_f32 v[118:119], v[118:119], v[228:229], v[176:177]
	s_waitcnt vmcnt(5)
	v_pk_fma_f32 v[114:115], v[114:115], v[232:233], v[132:133]
	v_pk_fma_f32 v[112:113], v[112:113], v[230:231], v[126:127]
.LBB0_652:
	v_mov_b32_e32 v121, v120
	v_mov_b32_e32 v126, v120
	v_mov_b32_e32 v127, v120
	v_pk_mul_f32 v[118:119], v[126:127], v[118:119]
	v_pk_mul_f32 v[126:127], v[126:127], v[114:115]
	v_pk_mul_f32 v[114:115], v[120:121], v[112:113]
	v_pk_mul_f32 v[116:117], v[120:121], v[116:117]
	s_waitcnt vmcnt(5)
	v_mov_b32_e32 v128, 0
	v_cvt_pk_bf16_f32 v112, v116, v117
	v_cvt_pk_bf16_f32 v113, v118, v119
	v_cvt_pk_bf16_f32 v114, v114, v115
	v_cvt_pk_bf16_f32 v115, v126, v127
	global_store_dwordx4 v[124:125], v[112:115], off offset:256
	v_mov_b32_e32 v129, 0
	v_mov_b32_e32 v130, 0
	v_mov_b32_e32 v131, 0
	v_mov_b32_e32 v126, 0
	v_mov_b32_e32 v127, 0
	v_mov_b32_e32 v124, 0
	v_mov_b32_e32 v125, 0
	v_mov_b32_e32 v226, 1.0
	v_mov_b32_e32 v227, 1.0
	v_mov_b32_e32 v228, 1.0
	v_mov_b32_e32 v229, 1.0
	v_mov_b32_e32 v230, 1.0
	v_mov_b32_e32 v231, 1.0
	v_mov_b32_e32 v232, 1.0
	v_mov_b32_e32 v233, 1.0
	s_and_saveexec_b64 s[4:5], s[46:47]
	s_cbranch_execz .LBB0_654
	v_add_u32_e32 v250, 0x20, v196
	v_lshlrev_b32_e32 v250, 6, v250
	v_and_b32_e32 v250, 0x7ffc0, v250
	global_load_dwordx4 v[218:221], v250, s[28:29] offset:32
	global_load_dwordx4 v[222:225], v250, s[28:29] offset:48
	global_load_dwordx4 v[226:229], v250, s[28:29]
	global_load_dwordx4 v[230:233], v250, s[28:29] offset:16
	s_waitcnt vmcnt(7)
	v_xor_b32_e32 v131, 0x80000000, v237
	v_xor_b32_e32 v130, 0x80000000, v236
	v_xor_b32_e32 v129, 0x80000000, v235
	v_xor_b32_e32 v128, 0x80000000, v234
	s_waitcnt vmcnt(6)
	v_xor_b32_e32 v144, 0x80000000, v241
	v_xor_b32_e32 v170, 0x80000000, v240
	v_xor_b32_e32 v171, 0x80000000, v239
	v_xor_b32_e32 v172, 0x80000000, v238
	v_cndmask_b32_e64 v128, v234, v128, s[8:9]
	v_cndmask_b32_e64 v129, v235, v129, s[8:9]
	v_cndmask_b32_e64 v130, v236, v130, s[8:9]
	v_cndmask_b32_e64 v131, v237, v131, s[8:9]
	v_cndmask_b32_e64 v126, v238, v172, s[8:9]
	v_cndmask_b32_e64 v127, v239, v171, s[8:9]
	v_cndmask_b32_e64 v124, v240, v170, s[8:9]
	v_cndmask_b32_e64 v125, v241, v144, s[8:9]
.LBB0_654:
	s_or_b64 exec, exec, s[4:5]
	s_waitcnt lgkmcnt(6)
	v_add_f32_e32 v132, v213, v214
	v_fmamk_f32 v132, v132, 0x3a800000, v195
	v_rsq_f32_e32 v132, v132
	s_nop 0
	v_pk_mul_f32 v[110:111], v[110:111], v[132:133] op_sel_hi:[1,0]
	v_pk_mul_f32 v[108:109], v[108:109], v[132:133] op_sel_hi:[1,0]
	v_pk_mul_f32 v[134:135], v[106:107], v[132:133] op_sel_hi:[1,0]
	s_and_b64 vcc, exec, s[12:13]
	v_pk_mul_f32 v[170:171], v[104:105], v[132:133] op_sel_hi:[1,0]
	s_cbranch_vccnz .LBB0_656
	ds_bpermute_b32 v104, v198, v108
	ds_bpermute_b32 v105, v198, v109
	ds_bpermute_b32 v106, v198, v170
	ds_bpermute_b32 v172, v198, v110
	ds_bpermute_b32 v173, v198, v111
	ds_bpermute_b32 v107, v198, v171
	ds_bpermute_b32 v174, v198, v134
	ds_bpermute_b32 v175, v198, v135
	s_waitcnt lgkmcnt(6)
	v_pk_mul_f32 v[104:105], v[128:129], v[104:105]
	s_waitcnt lgkmcnt(3)
	v_pk_mul_f32 v[172:173], v[130:131], v[172:173]
	s_waitcnt vmcnt(5)
	v_pk_fma_f32 v[108:109], v[108:109], v[242:243], v[104:105]
	s_waitcnt lgkmcnt(2)
	v_pk_mul_f32 v[104:105], v[126:127], v[106:107]
	s_waitcnt lgkmcnt(0)
	v_pk_mul_f32 v[106:107], v[124:125], v[174:175]
	v_pk_fma_f32 v[110:111], v[110:111], v[244:245], v[172:173]
	s_waitcnt vmcnt(4)
	v_pk_fma_f32 v[134:135], v[134:135], v[248:249], v[106:107]
	v_pk_fma_f32 v[170:171], v[170:171], v[246:247], v[104:105]
.LBB0_656:
	v_lshlrev_b64 v[104:105], 11, v[168:169]
	v_mov_b32_e32 v106, v120
	v_mov_b32_e32 v107, v120
	v_pk_mul_f32 v[108:109], v[120:121], v[108:109]
	v_lshl_add_u64 v[104:105], v[122:123], 0, v[104:105]
	v_pk_mul_f32 v[110:111], v[106:107], v[110:111]
	v_cvt_pk_bf16_f32 v108, v108, v109
	v_mov_b32_e32 v133, v132
	v_cvt_pk_bf16_f32 v109, v110, v111
	v_pk_mul_f32 v[134:135], v[106:107], v[134:135]
	v_pk_mul_f32 v[168:169], v[120:121], v[170:171]
	v_pk_mul_f32 v[100:101], v[100:101], v[132:133]
	v_cvt_pk_bf16_f32 v110, v168, v169
	v_cvt_pk_bf16_f32 v111, v134, v135
	global_store_dwordx4 v[104:105], v[108:111], off
	s_and_b64 vcc, exec, s[12:13]
	v_pk_mul_f32 v[96:97], v[96:97], v[132:133]
	v_mov_b32_e32 v108, v132
	v_mov_b32_e32 v109, v132
	v_pk_mul_f32 v[102:103], v[102:103], v[108:109]
	v_pk_mul_f32 v[98:99], v[98:99], v[108:109]
	s_cbranch_vccnz .LBB0_658
	ds_bpermute_b32 v108, v198, v100
	ds_bpermute_b32 v109, v198, v101
	ds_bpermute_b32 v110, v198, v96
	ds_bpermute_b32 v132, v198, v102
	ds_bpermute_b32 v133, v198, v103
	ds_bpermute_b32 v111, v198, v97
	ds_bpermute_b32 v134, v198, v98
	ds_bpermute_b32 v135, v198, v99
	s_waitcnt lgkmcnt(6)
	v_pk_mul_f32 v[108:109], v[128:129], v[108:109]
	s_waitcnt lgkmcnt(3)
	v_pk_mul_f32 v[128:129], v[130:131], v[132:133]
	s_waitcnt vmcnt(6)
	v_pk_fma_f32 v[100:101], v[100:101], v[242:243], v[108:109]
	s_waitcnt lgkmcnt(2)
	v_pk_mul_f32 v[108:109], v[126:127], v[110:111]
	s_waitcnt lgkmcnt(0)
	v_pk_mul_f32 v[110:111], v[124:125], v[134:135]
	v_pk_fma_f32 v[102:103], v[102:103], v[244:245], v[128:129]
	s_waitcnt vmcnt(5)
	v_pk_fma_f32 v[98:99], v[98:99], v[248:249], v[110:111]
	v_pk_fma_f32 v[96:97], v[96:97], v[246:247], v[108:109]
.LBB0_658:
	v_pk_mul_f32 v[102:103], v[106:107], v[102:103]
	v_pk_mul_f32 v[106:107], v[106:107], v[98:99]
	v_pk_mul_f32 v[98:99], v[120:121], v[96:97]
	v_pk_mul_f32 v[100:101], v[120:121], v[100:101]
	v_mov_b32_e32 v108, 0
	v_cvt_pk_bf16_f32 v96, v100, v101
	v_cvt_pk_bf16_f32 v97, v102, v103
	v_cvt_pk_bf16_f32 v98, v98, v99
	v_cvt_pk_bf16_f32 v99, v106, v107
	global_store_dwordx4 v[104:105], v[96:99], off offset:256
	v_mov_b32_e32 v109, 0
	v_mov_b32_e32 v110, 0
	v_mov_b32_e32 v111, 0
	v_mov_b32_e32 v106, 0
	v_mov_b32_e32 v107, 0
	v_mov_b32_e32 v104, 0
	v_mov_b32_e32 v105, 0
	v_mov_b32_e32 v242, 1.0
	v_mov_b32_e32 v243, 1.0
	v_mov_b32_e32 v244, 1.0
	v_mov_b32_e32 v245, 1.0
	v_mov_b32_e32 v246, 1.0
	v_mov_b32_e32 v247, 1.0
	v_mov_b32_e32 v248, 1.0
	v_mov_b32_e32 v249, 1.0
	s_and_saveexec_b64 s[4:5], s[46:47]
	s_cbranch_execz .LBB0_660
	v_add_u32_e32 v250, 0x30, v196
	v_lshlrev_b32_e32 v250, 6, v250
	v_and_b32_e32 v250, 0x7ffc0, v250
	global_load_dwordx4 v[234:237], v250, s[28:29] offset:32
	global_load_dwordx4 v[238:241], v250, s[28:29] offset:48
	global_load_dwordx4 v[242:245], v250, s[28:29]
	global_load_dwordx4 v[246:249], v250, s[28:29] offset:16
	s_waitcnt vmcnt(7)
	v_xor_b32_e32 v111, 0x80000000, v221
	v_xor_b32_e32 v110, 0x80000000, v220
	v_xor_b32_e32 v109, 0x80000000, v219
	v_xor_b32_e32 v108, 0x80000000, v218
	s_waitcnt vmcnt(6)
	v_xor_b32_e32 v116, 0x80000000, v225
	v_xor_b32_e32 v117, 0x80000000, v224
	v_xor_b32_e32 v118, 0x80000000, v223
	v_xor_b32_e32 v119, 0x80000000, v222
	v_cndmask_b32_e64 v108, v218, v108, s[8:9]
	v_cndmask_b32_e64 v109, v219, v109, s[8:9]
	v_cndmask_b32_e64 v110, v220, v110, s[8:9]
	v_cndmask_b32_e64 v111, v221, v111, s[8:9]
	v_cndmask_b32_e64 v106, v222, v119, s[8:9]
	v_cndmask_b32_e64 v107, v223, v118, s[8:9]
	v_cndmask_b32_e64 v104, v224, v117, s[8:9]
	v_cndmask_b32_e64 v105, v225, v116, s[8:9]
.LBB0_660:
	s_or_b64 exec, exec, s[4:5]
	s_waitcnt vmcnt(6) lgkmcnt(5)
	v_add_f32_e32 v112, v211, v212
	v_fmamk_f32 v112, v112, 0x3a800000, v195
	v_rsq_f32_e32 v112, v112
	s_nop 0
	v_pk_mul_f32 v[94:95], v[94:95], v[112:113] op_sel_hi:[1,0]
	v_pk_mul_f32 v[92:93], v[92:93], v[112:113] op_sel_hi:[1,0]
	v_pk_mul_f32 v[114:115], v[90:91], v[112:113] op_sel_hi:[1,0]
	s_and_b64 vcc, exec, s[12:13]
	v_pk_mul_f32 v[116:117], v[88:89], v[112:113] op_sel_hi:[1,0]
	s_cbranch_vccnz .LBB0_662
	ds_bpermute_b32 v88, v198, v92
	ds_bpermute_b32 v89, v198, v93
	ds_bpermute_b32 v90, v198, v116
	ds_bpermute_b32 v118, v198, v94
	ds_bpermute_b32 v119, v198, v95
	ds_bpermute_b32 v91, v198, v117
	ds_bpermute_b32 v124, v198, v114
	ds_bpermute_b32 v125, v198, v115
	s_waitcnt lgkmcnt(6)
	v_pk_mul_f32 v[88:89], v[108:109], v[88:89]
	s_waitcnt lgkmcnt(3)
	v_pk_mul_f32 v[118:119], v[110:111], v[118:119]
	s_waitcnt vmcnt(5)
	v_pk_fma_f32 v[92:93], v[92:93], v[226:227], v[88:89]
	s_waitcnt lgkmcnt(2)
	v_pk_mul_f32 v[88:89], v[106:107], v[90:91]
	s_waitcnt lgkmcnt(0)
	v_pk_mul_f32 v[90:91], v[104:105], v[124:125]
	v_pk_fma_f32 v[94:95], v[94:95], v[228:229], v[118:119]
	s_waitcnt vmcnt(4)
	v_pk_fma_f32 v[114:115], v[114:115], v[232:233], v[90:91]
	v_pk_fma_f32 v[116:117], v[116:117], v[230:231], v[88:89]
.LBB0_662:
	v_lshlrev_b64 v[88:89], 11, v[166:167]
	v_mov_b32_e32 v90, v120
	v_mov_b32_e32 v91, v120
	v_pk_mul_f32 v[92:93], v[120:121], v[92:93]
	v_lshl_add_u64 v[88:89], v[122:123], 0, v[88:89]
	v_pk_mul_f32 v[94:95], v[90:91], v[94:95]
	v_cvt_pk_bf16_f32 v92, v92, v93
	v_mov_b32_e32 v113, v112
	v_cvt_pk_bf16_f32 v93, v94, v95
	v_pk_mul_f32 v[114:115], v[90:91], v[114:115]
	v_pk_mul_f32 v[116:117], v[120:121], v[116:117]
	v_pk_mul_f32 v[84:85], v[84:85], v[112:113]
	v_cvt_pk_bf16_f32 v94, v116, v117
	v_cvt_pk_bf16_f32 v95, v114, v115
	global_store_dwordx4 v[88:89], v[92:95], off
	s_and_b64 vcc, exec, s[12:13]
	v_pk_mul_f32 v[80:81], v[80:81], v[112:113]
	v_mov_b32_e32 v92, v112
	v_mov_b32_e32 v93, v112
	v_pk_mul_f32 v[86:87], v[86:87], v[92:93]
	v_pk_mul_f32 v[82:83], v[82:83], v[92:93]
	s_cbranch_vccnz .LBB0_664
	ds_bpermute_b32 v92, v198, v84
	ds_bpermute_b32 v93, v198, v85
	ds_bpermute_b32 v94, v198, v80
	ds_bpermute_b32 v112, v198, v86
	ds_bpermute_b32 v113, v198, v87
	ds_bpermute_b32 v95, v198, v81
	ds_bpermute_b32 v114, v198, v82
	ds_bpermute_b32 v115, v198, v83
	s_waitcnt lgkmcnt(6)
	v_pk_mul_f32 v[92:93], v[108:109], v[92:93]
	s_waitcnt lgkmcnt(3)
	v_pk_mul_f32 v[108:109], v[110:111], v[112:113]
	s_waitcnt vmcnt(6)
	v_pk_fma_f32 v[84:85], v[84:85], v[226:227], v[92:93]
	s_waitcnt lgkmcnt(2)
	v_pk_mul_f32 v[92:93], v[106:107], v[94:95]
	s_waitcnt lgkmcnt(0)
	v_pk_mul_f32 v[94:95], v[104:105], v[114:115]
	v_pk_fma_f32 v[86:87], v[86:87], v[228:229], v[108:109]
	s_waitcnt vmcnt(5)
	v_pk_fma_f32 v[82:83], v[82:83], v[232:233], v[94:95]
	v_pk_fma_f32 v[80:81], v[80:81], v[230:231], v[92:93]
.LBB0_664:
	v_pk_mul_f32 v[86:87], v[90:91], v[86:87]
	v_pk_mul_f32 v[90:91], v[90:91], v[82:83]
	v_pk_mul_f32 v[82:83], v[120:121], v[80:81]
	v_pk_mul_f32 v[84:85], v[120:121], v[84:85]
	v_mov_b32_e32 v92, 0
	v_cvt_pk_bf16_f32 v80, v84, v85
	v_cvt_pk_bf16_f32 v81, v86, v87
	v_cvt_pk_bf16_f32 v82, v82, v83
	v_cvt_pk_bf16_f32 v83, v90, v91
	global_store_dwordx4 v[88:89], v[80:83], off offset:256
	v_mov_b32_e32 v93, 0
	v_mov_b32_e32 v94, 0
	v_mov_b32_e32 v95, 0
	v_mov_b32_e32 v90, 0
	v_mov_b32_e32 v91, 0
	v_mov_b32_e32 v88, 0
	v_mov_b32_e32 v89, 0
	v_mov_b32_e32 v226, 1.0
	v_mov_b32_e32 v227, 1.0
	v_mov_b32_e32 v228, 1.0
	v_mov_b32_e32 v229, 1.0
	v_mov_b32_e32 v230, 1.0
	v_mov_b32_e32 v231, 1.0
	v_mov_b32_e32 v232, 1.0
	v_mov_b32_e32 v233, 1.0
	s_and_saveexec_b64 s[4:5], s[46:47]
	s_cbranch_execz .LBB0_666
	v_add_u32_e32 v250, 0x80, v196
	v_lshlrev_b32_e32 v250, 6, v250
	v_and_b32_e32 v250, 0x7ffc0, v250
	global_load_dwordx4 v[218:221], v250, s[28:29] offset:32
	global_load_dwordx4 v[222:225], v250, s[28:29] offset:48
	global_load_dwordx4 v[226:229], v250, s[28:29]
	global_load_dwordx4 v[230:233], v250, s[28:29] offset:16
	s_waitcnt vmcnt(7)
	v_xor_b32_e32 v95, 0x80000000, v237
	v_xor_b32_e32 v94, 0x80000000, v236
	v_xor_b32_e32 v93, 0x80000000, v235
	v_xor_b32_e32 v92, 0x80000000, v234
	s_waitcnt vmcnt(6)
	v_xor_b32_e32 v100, 0x80000000, v241
	v_xor_b32_e32 v101, 0x80000000, v240
	v_xor_b32_e32 v102, 0x80000000, v239
	v_xor_b32_e32 v103, 0x80000000, v238
	v_cndmask_b32_e64 v92, v234, v92, s[8:9]
	v_cndmask_b32_e64 v93, v235, v93, s[8:9]
	v_cndmask_b32_e64 v94, v236, v94, s[8:9]
	v_cndmask_b32_e64 v95, v237, v95, s[8:9]
	v_cndmask_b32_e64 v90, v238, v103, s[8:9]
	v_cndmask_b32_e64 v91, v239, v102, s[8:9]
	v_cndmask_b32_e64 v88, v240, v101, s[8:9]
	v_cndmask_b32_e64 v89, v241, v100, s[8:9]
.LBB0_666:
	s_or_b64 exec, exec, s[4:5]
	s_waitcnt vmcnt(6) lgkmcnt(4)
	v_add_f32_e32 v96, v209, v210
	v_fmamk_f32 v96, v96, 0x3a800000, v195
	v_rsq_f32_e32 v96, v96
	s_nop 0
	v_pk_mul_f32 v[78:79], v[78:79], v[96:97] op_sel_hi:[1,0]
	v_pk_mul_f32 v[76:77], v[76:77], v[96:97] op_sel_hi:[1,0]
	v_pk_mul_f32 v[98:99], v[74:75], v[96:97] op_sel_hi:[1,0]
	s_and_b64 vcc, exec, s[12:13]
	v_pk_mul_f32 v[100:101], v[72:73], v[96:97] op_sel_hi:[1,0]
	s_cbranch_vccnz .LBB0_668
	ds_bpermute_b32 v72, v198, v76
	ds_bpermute_b32 v73, v198, v77
	ds_bpermute_b32 v74, v198, v100
	ds_bpermute_b32 v102, v198, v78
	ds_bpermute_b32 v103, v198, v79
	ds_bpermute_b32 v75, v198, v101
	ds_bpermute_b32 v104, v198, v98
	ds_bpermute_b32 v105, v198, v99
	s_waitcnt lgkmcnt(6)
	v_pk_mul_f32 v[72:73], v[92:93], v[72:73]
	s_waitcnt lgkmcnt(3)
	v_pk_mul_f32 v[102:103], v[94:95], v[102:103]
	s_waitcnt vmcnt(5)
	v_pk_fma_f32 v[76:77], v[76:77], v[242:243], v[72:73]
	s_waitcnt lgkmcnt(2)
	v_pk_mul_f32 v[72:73], v[90:91], v[74:75]
	s_waitcnt lgkmcnt(0)
	v_pk_mul_f32 v[74:75], v[88:89], v[104:105]
	v_pk_fma_f32 v[78:79], v[78:79], v[244:245], v[102:103]
	s_waitcnt vmcnt(4)
	v_pk_fma_f32 v[98:99], v[98:99], v[248:249], v[74:75]
	v_pk_fma_f32 v[100:101], v[100:101], v[246:247], v[72:73]
.LBB0_668:
	v_lshlrev_b64 v[72:73], 11, v[164:165]
	v_mov_b32_e32 v74, v120
	v_mov_b32_e32 v75, v120
	v_pk_mul_f32 v[76:77], v[120:121], v[76:77]
	v_lshl_add_u64 v[72:73], v[122:123], 0, v[72:73]
	v_pk_mul_f32 v[78:79], v[74:75], v[78:79]
	v_cvt_pk_bf16_f32 v76, v76, v77
	v_mov_b32_e32 v97, v96
	v_cvt_pk_bf16_f32 v77, v78, v79
	v_pk_mul_f32 v[98:99], v[74:75], v[98:99]
	v_pk_mul_f32 v[100:101], v[120:121], v[100:101]
	v_pk_mul_f32 v[68:69], v[68:69], v[96:97]
	v_cvt_pk_bf16_f32 v78, v100, v101
	v_cvt_pk_bf16_f32 v79, v98, v99
	global_store_dwordx4 v[72:73], v[76:79], off
	s_and_b64 vcc, exec, s[12:13]
	v_pk_mul_f32 v[64:65], v[64:65], v[96:97]
	v_mov_b32_e32 v76, v96
	v_mov_b32_e32 v77, v96
	v_pk_mul_f32 v[70:71], v[70:71], v[76:77]
	v_pk_mul_f32 v[66:67], v[66:67], v[76:77]
	s_cbranch_vccnz .LBB0_670
	ds_bpermute_b32 v76, v198, v68
	ds_bpermute_b32 v77, v198, v69
	ds_bpermute_b32 v78, v198, v64
	ds_bpermute_b32 v96, v198, v70
	ds_bpermute_b32 v97, v198, v71
	ds_bpermute_b32 v79, v198, v65
	ds_bpermute_b32 v98, v198, v66
	ds_bpermute_b32 v99, v198, v67
	s_waitcnt lgkmcnt(6)
	v_pk_mul_f32 v[76:77], v[92:93], v[76:77]
	s_waitcnt lgkmcnt(3)
	v_pk_mul_f32 v[92:93], v[94:95], v[96:97]
	s_waitcnt vmcnt(6)
	v_pk_fma_f32 v[68:69], v[68:69], v[242:243], v[76:77]
	s_waitcnt lgkmcnt(2)
	v_pk_mul_f32 v[76:77], v[90:91], v[78:79]
	s_waitcnt lgkmcnt(0)
	v_pk_mul_f32 v[78:79], v[88:89], v[98:99]
	v_pk_fma_f32 v[70:71], v[70:71], v[244:245], v[92:93]
	s_waitcnt vmcnt(5)
	v_pk_fma_f32 v[66:67], v[66:67], v[248:249], v[78:79]
	v_pk_fma_f32 v[64:65], v[64:65], v[246:247], v[76:77]
.LBB0_670:
	v_pk_mul_f32 v[70:71], v[74:75], v[70:71]
	v_pk_mul_f32 v[74:75], v[74:75], v[66:67]
	v_pk_mul_f32 v[66:67], v[120:121], v[64:65]
	v_pk_mul_f32 v[68:69], v[120:121], v[68:69]
	v_mov_b32_e32 v76, 0
	v_cvt_pk_bf16_f32 v64, v68, v69
	v_cvt_pk_bf16_f32 v65, v70, v71
	v_cvt_pk_bf16_f32 v66, v66, v67
	v_cvt_pk_bf16_f32 v67, v74, v75
	global_store_dwordx4 v[72:73], v[64:67], off offset:256
	v_mov_b32_e32 v77, 0
	v_mov_b32_e32 v78, 0
	v_mov_b32_e32 v79, 0
	v_mov_b32_e32 v74, 0
	v_mov_b32_e32 v75, 0
	v_mov_b32_e32 v72, 0
	v_mov_b32_e32 v73, 0
	v_mov_b32_e32 v242, 1.0
	v_mov_b32_e32 v243, 1.0
	v_mov_b32_e32 v244, 1.0
	v_mov_b32_e32 v245, 1.0
	v_mov_b32_e32 v246, 1.0
	v_mov_b32_e32 v247, 1.0
	v_mov_b32_e32 v248, 1.0
	v_mov_b32_e32 v249, 1.0
	s_and_saveexec_b64 s[4:5], s[46:47]
	s_cbranch_execz .LBB0_672
	v_add_u32_e32 v250, 0x90, v196
	v_lshlrev_b32_e32 v250, 6, v250
	v_and_b32_e32 v250, 0x7ffc0, v250
	global_load_dwordx4 v[234:237], v250, s[28:29] offset:32
	global_load_dwordx4 v[238:241], v250, s[28:29] offset:48
	global_load_dwordx4 v[242:245], v250, s[28:29]
	global_load_dwordx4 v[246:249], v250, s[28:29] offset:16
	s_waitcnt vmcnt(7)
	v_xor_b32_e32 v79, 0x80000000, v221
	v_xor_b32_e32 v78, 0x80000000, v220
	v_xor_b32_e32 v77, 0x80000000, v219
	v_xor_b32_e32 v76, 0x80000000, v218
	s_waitcnt vmcnt(6)
	v_xor_b32_e32 v84, 0x80000000, v225
	v_xor_b32_e32 v85, 0x80000000, v224
	v_xor_b32_e32 v86, 0x80000000, v223
	v_xor_b32_e32 v87, 0x80000000, v222
	v_cndmask_b32_e64 v76, v218, v76, s[8:9]
	v_cndmask_b32_e64 v77, v219, v77, s[8:9]
	v_cndmask_b32_e64 v78, v220, v78, s[8:9]
	v_cndmask_b32_e64 v79, v221, v79, s[8:9]
	v_cndmask_b32_e64 v74, v222, v87, s[8:9]
	v_cndmask_b32_e64 v75, v223, v86, s[8:9]
	v_cndmask_b32_e64 v72, v224, v85, s[8:9]
	v_cndmask_b32_e64 v73, v225, v84, s[8:9]
.LBB0_672:
	s_or_b64 exec, exec, s[4:5]
	s_waitcnt vmcnt(6) lgkmcnt(3)
	v_add_f32_e32 v80, v207, v208
	v_fmamk_f32 v80, v80, 0x3a800000, v195
	v_rsq_f32_e32 v80, v80
	s_nop 0
	v_pk_mul_f32 v[62:63], v[62:63], v[80:81] op_sel_hi:[1,0]
	v_pk_mul_f32 v[60:61], v[60:61], v[80:81] op_sel_hi:[1,0]
	v_pk_mul_f32 v[82:83], v[58:59], v[80:81] op_sel_hi:[1,0]
	s_and_b64 vcc, exec, s[12:13]
	v_pk_mul_f32 v[84:85], v[56:57], v[80:81] op_sel_hi:[1,0]
	s_cbranch_vccnz .LBB0_674
	ds_bpermute_b32 v56, v198, v60
	ds_bpermute_b32 v57, v198, v61
	ds_bpermute_b32 v58, v198, v84
	ds_bpermute_b32 v86, v198, v62
	ds_bpermute_b32 v87, v198, v63
	ds_bpermute_b32 v59, v198, v85
	ds_bpermute_b32 v88, v198, v82
	ds_bpermute_b32 v89, v198, v83
	s_waitcnt lgkmcnt(6)
	v_pk_mul_f32 v[56:57], v[76:77], v[56:57]
	s_waitcnt lgkmcnt(3)
	v_pk_mul_f32 v[86:87], v[78:79], v[86:87]
	s_waitcnt vmcnt(5)
	v_pk_fma_f32 v[60:61], v[60:61], v[226:227], v[56:57]
	s_waitcnt lgkmcnt(2)
	v_pk_mul_f32 v[56:57], v[74:75], v[58:59]
	s_waitcnt lgkmcnt(0)
	v_pk_mul_f32 v[58:59], v[72:73], v[88:89]
	v_pk_fma_f32 v[62:63], v[62:63], v[228:229], v[86:87]
	s_waitcnt vmcnt(4)
	v_pk_fma_f32 v[82:83], v[82:83], v[232:233], v[58:59]
	v_pk_fma_f32 v[84:85], v[84:85], v[230:231], v[56:57]
.LBB0_674:
	v_lshlrev_b64 v[56:57], 11, v[162:163]
	v_mov_b32_e32 v58, v120
	v_mov_b32_e32 v59, v120
	v_pk_mul_f32 v[60:61], v[120:121], v[60:61]
	v_lshl_add_u64 v[56:57], v[122:123], 0, v[56:57]
	v_pk_mul_f32 v[62:63], v[58:59], v[62:63]
	v_cvt_pk_bf16_f32 v60, v60, v61
	v_mov_b32_e32 v81, v80
	v_cvt_pk_bf16_f32 v61, v62, v63
	v_pk_mul_f32 v[82:83], v[58:59], v[82:83]
	v_pk_mul_f32 v[84:85], v[120:121], v[84:85]
	v_pk_mul_f32 v[52:53], v[52:53], v[80:81]
	v_cvt_pk_bf16_f32 v62, v84, v85
	v_cvt_pk_bf16_f32 v63, v82, v83
	global_store_dwordx4 v[56:57], v[60:63], off
	s_and_b64 vcc, exec, s[12:13]
	v_pk_mul_f32 v[48:49], v[48:49], v[80:81]
	v_mov_b32_e32 v60, v80
	v_mov_b32_e32 v61, v80
	v_pk_mul_f32 v[54:55], v[54:55], v[60:61]
	v_pk_mul_f32 v[50:51], v[50:51], v[60:61]
	s_cbranch_vccnz .LBB0_676
	ds_bpermute_b32 v60, v198, v52
	ds_bpermute_b32 v61, v198, v53
	ds_bpermute_b32 v62, v198, v48
	ds_bpermute_b32 v80, v198, v54
	ds_bpermute_b32 v81, v198, v55
	ds_bpermute_b32 v63, v198, v49
	ds_bpermute_b32 v82, v198, v50
	ds_bpermute_b32 v83, v198, v51
	s_waitcnt lgkmcnt(6)
	v_pk_mul_f32 v[60:61], v[76:77], v[60:61]
	s_waitcnt lgkmcnt(3)
	v_pk_mul_f32 v[76:77], v[78:79], v[80:81]
	s_waitcnt vmcnt(6)
	v_pk_fma_f32 v[52:53], v[52:53], v[226:227], v[60:61]
	s_waitcnt lgkmcnt(2)
	v_pk_mul_f32 v[60:61], v[74:75], v[62:63]
	s_waitcnt lgkmcnt(0)
	v_pk_mul_f32 v[62:63], v[72:73], v[82:83]
	v_pk_fma_f32 v[54:55], v[54:55], v[228:229], v[76:77]
	s_waitcnt vmcnt(5)
	v_pk_fma_f32 v[50:51], v[50:51], v[232:233], v[62:63]
	v_pk_fma_f32 v[48:49], v[48:49], v[230:231], v[60:61]
.LBB0_676:
	v_pk_mul_f32 v[54:55], v[58:59], v[54:55]
	v_pk_mul_f32 v[58:59], v[58:59], v[50:51]
	v_pk_mul_f32 v[50:51], v[120:121], v[48:49]
	v_pk_mul_f32 v[52:53], v[120:121], v[52:53]
	v_mov_b32_e32 v60, 0
	v_cvt_pk_bf16_f32 v48, v52, v53
	v_cvt_pk_bf16_f32 v49, v54, v55
	v_cvt_pk_bf16_f32 v50, v50, v51
	v_cvt_pk_bf16_f32 v51, v58, v59
	global_store_dwordx4 v[56:57], v[48:51], off offset:256
	v_mov_b32_e32 v61, 0
	v_mov_b32_e32 v62, 0
	v_mov_b32_e32 v63, 0
	v_mov_b32_e32 v58, 0
	v_mov_b32_e32 v59, 0
	v_mov_b32_e32 v56, 0
	v_mov_b32_e32 v57, 0
	v_mov_b32_e32 v226, 1.0
	v_mov_b32_e32 v227, 1.0
	v_mov_b32_e32 v228, 1.0
	v_mov_b32_e32 v229, 1.0
	v_mov_b32_e32 v230, 1.0
	v_mov_b32_e32 v231, 1.0
	v_mov_b32_e32 v232, 1.0
	v_mov_b32_e32 v233, 1.0
	s_and_saveexec_b64 s[4:5], s[46:47]
	s_cbranch_execz .LBB0_678
	v_add_u32_e32 v250, 0xa0, v196
	v_lshlrev_b32_e32 v250, 6, v250
	v_and_b32_e32 v250, 0x7ffc0, v250
	global_load_dwordx4 v[218:221], v250, s[28:29] offset:32
	global_load_dwordx4 v[222:225], v250, s[28:29] offset:48
	global_load_dwordx4 v[226:229], v250, s[28:29]
	global_load_dwordx4 v[230:233], v250, s[28:29] offset:16
	s_waitcnt vmcnt(7)
	v_xor_b32_e32 v63, 0x80000000, v237
	v_xor_b32_e32 v62, 0x80000000, v236
	v_xor_b32_e32 v61, 0x80000000, v235
	v_xor_b32_e32 v60, 0x80000000, v234
	s_waitcnt vmcnt(6)
	v_xor_b32_e32 v68, 0x80000000, v241
	v_xor_b32_e32 v69, 0x80000000, v240
	v_xor_b32_e32 v70, 0x80000000, v239
	v_xor_b32_e32 v71, 0x80000000, v238
	v_cndmask_b32_e64 v60, v234, v60, s[8:9]
	v_cndmask_b32_e64 v61, v235, v61, s[8:9]
	v_cndmask_b32_e64 v62, v236, v62, s[8:9]
	v_cndmask_b32_e64 v63, v237, v63, s[8:9]
	v_cndmask_b32_e64 v58, v238, v71, s[8:9]
	v_cndmask_b32_e64 v59, v239, v70, s[8:9]
	v_cndmask_b32_e64 v56, v240, v69, s[8:9]
	v_cndmask_b32_e64 v57, v241, v68, s[8:9]
.LBB0_678:
	s_or_b64 exec, exec, s[4:5]
	s_waitcnt vmcnt(6) lgkmcnt(2)
	v_add_f32_e32 v64, v205, v206
	v_fmamk_f32 v64, v64, 0x3a800000, v195
	v_rsq_f32_e32 v64, v64
	s_nop 0
	v_pk_mul_f32 v[46:47], v[46:47], v[64:65] op_sel_hi:[1,0]
	v_pk_mul_f32 v[44:45], v[44:45], v[64:65] op_sel_hi:[1,0]
	v_pk_mul_f32 v[66:67], v[42:43], v[64:65] op_sel_hi:[1,0]
	s_and_b64 vcc, exec, s[12:13]
	v_pk_mul_f32 v[68:69], v[40:41], v[64:65] op_sel_hi:[1,0]
	s_cbranch_vccnz .LBB0_680
	ds_bpermute_b32 v40, v198, v44
	ds_bpermute_b32 v41, v198, v45
	ds_bpermute_b32 v42, v198, v68
	ds_bpermute_b32 v70, v198, v46
	ds_bpermute_b32 v71, v198, v47
	ds_bpermute_b32 v43, v198, v69
	ds_bpermute_b32 v72, v198, v66
	ds_bpermute_b32 v73, v198, v67
	s_waitcnt lgkmcnt(6)
	v_pk_mul_f32 v[40:41], v[60:61], v[40:41]
	s_waitcnt lgkmcnt(3)
	v_pk_mul_f32 v[70:71], v[62:63], v[70:71]
	s_waitcnt vmcnt(5)
	v_pk_fma_f32 v[44:45], v[44:45], v[242:243], v[40:41]
	s_waitcnt lgkmcnt(2)
	v_pk_mul_f32 v[40:41], v[58:59], v[42:43]
	s_waitcnt lgkmcnt(0)
	v_pk_mul_f32 v[42:43], v[56:57], v[72:73]
	v_pk_fma_f32 v[46:47], v[46:47], v[244:245], v[70:71]
	s_waitcnt vmcnt(4)
	v_pk_fma_f32 v[66:67], v[66:67], v[248:249], v[42:43]
	v_pk_fma_f32 v[68:69], v[68:69], v[246:247], v[40:41]
.LBB0_680:
	v_lshlrev_b64 v[40:41], 11, v[160:161]
	v_mov_b32_e32 v42, v120
	v_mov_b32_e32 v43, v120
	v_pk_mul_f32 v[44:45], v[120:121], v[44:45]
	v_lshl_add_u64 v[40:41], v[122:123], 0, v[40:41]
	v_pk_mul_f32 v[46:47], v[42:43], v[46:47]
	v_cvt_pk_bf16_f32 v44, v44, v45
	v_mov_b32_e32 v65, v64
	v_cvt_pk_bf16_f32 v45, v46, v47
	v_pk_mul_f32 v[66:67], v[42:43], v[66:67]
	v_pk_mul_f32 v[68:69], v[120:121], v[68:69]
	v_pk_mul_f32 v[36:37], v[36:37], v[64:65]
	v_cvt_pk_bf16_f32 v46, v68, v69
	v_cvt_pk_bf16_f32 v47, v66, v67
	global_store_dwordx4 v[40:41], v[44:47], off
	s_and_b64 vcc, exec, s[12:13]
	v_pk_mul_f32 v[32:33], v[32:33], v[64:65]
	v_mov_b32_e32 v44, v64
	v_mov_b32_e32 v45, v64
	v_pk_mul_f32 v[38:39], v[38:39], v[44:45]
	v_pk_mul_f32 v[34:35], v[34:35], v[44:45]
	s_cbranch_vccnz .LBB0_682
	ds_bpermute_b32 v44, v198, v36
	ds_bpermute_b32 v45, v198, v37
	ds_bpermute_b32 v46, v198, v32
	ds_bpermute_b32 v64, v198, v38
	ds_bpermute_b32 v65, v198, v39
	ds_bpermute_b32 v47, v198, v33
	ds_bpermute_b32 v66, v198, v34
	ds_bpermute_b32 v67, v198, v35
	s_waitcnt lgkmcnt(6)
	v_pk_mul_f32 v[44:45], v[60:61], v[44:45]
	s_waitcnt lgkmcnt(3)
	v_pk_mul_f32 v[60:61], v[62:63], v[64:65]
	s_waitcnt vmcnt(6)
	v_pk_fma_f32 v[36:37], v[36:37], v[242:243], v[44:45]
	s_waitcnt lgkmcnt(2)
	v_pk_mul_f32 v[44:45], v[58:59], v[46:47]
	s_waitcnt lgkmcnt(0)
	v_pk_mul_f32 v[46:47], v[56:57], v[66:67]
	v_pk_fma_f32 v[38:39], v[38:39], v[244:245], v[60:61]
	s_waitcnt vmcnt(5)
	v_pk_fma_f32 v[34:35], v[34:35], v[248:249], v[46:47]
	v_pk_fma_f32 v[32:33], v[32:33], v[246:247], v[44:45]
.LBB0_682:
	v_pk_mul_f32 v[38:39], v[42:43], v[38:39]
	v_pk_mul_f32 v[42:43], v[42:43], v[34:35]
	v_pk_mul_f32 v[34:35], v[120:121], v[32:33]
	v_pk_mul_f32 v[36:37], v[120:121], v[36:37]
	v_mov_b32_e32 v44, 0
	v_cvt_pk_bf16_f32 v32, v36, v37
	v_cvt_pk_bf16_f32 v33, v38, v39
	v_cvt_pk_bf16_f32 v34, v34, v35
	v_cvt_pk_bf16_f32 v35, v42, v43
	global_store_dwordx4 v[40:41], v[32:35], off offset:256
	v_mov_b32_e32 v45, 0
	v_mov_b32_e32 v46, 0
	v_mov_b32_e32 v47, 0
	v_mov_b32_e32 v42, 0
	v_mov_b32_e32 v43, 0
	v_mov_b32_e32 v40, 0
	v_mov_b32_e32 v41, 0
	v_mov_b32_e32 v242, 1.0
	v_mov_b32_e32 v243, 1.0
	v_mov_b32_e32 v244, 1.0
	v_mov_b32_e32 v245, 1.0
	v_mov_b32_e32 v246, 1.0
	v_mov_b32_e32 v247, 1.0
	v_mov_b32_e32 v248, 1.0
	v_mov_b32_e32 v249, 1.0
	s_and_saveexec_b64 s[4:5], s[46:47]
	s_cbranch_execz .LBB0_684
	v_add_u32_e32 v250, 0xb0, v196
	v_lshlrev_b32_e32 v250, 6, v250
	v_and_b32_e32 v250, 0x7ffc0, v250
	global_load_dwordx4 v[234:237], v250, s[28:29] offset:32
	global_load_dwordx4 v[238:241], v250, s[28:29] offset:48
	global_load_dwordx4 v[242:245], v250, s[28:29]
	global_load_dwordx4 v[246:249], v250, s[28:29] offset:16
	s_waitcnt vmcnt(7)
	v_xor_b32_e32 v47, 0x80000000, v221
	v_xor_b32_e32 v46, 0x80000000, v220
	v_xor_b32_e32 v45, 0x80000000, v219
	v_xor_b32_e32 v44, 0x80000000, v218
	s_waitcnt vmcnt(6)
	v_xor_b32_e32 v52, 0x80000000, v225
	v_xor_b32_e32 v53, 0x80000000, v224
	v_xor_b32_e32 v54, 0x80000000, v223
	v_xor_b32_e32 v55, 0x80000000, v222
	v_cndmask_b32_e64 v44, v218, v44, s[8:9]
	v_cndmask_b32_e64 v45, v219, v45, s[8:9]
	v_cndmask_b32_e64 v46, v220, v46, s[8:9]
	v_cndmask_b32_e64 v47, v221, v47, s[8:9]
	v_cndmask_b32_e64 v42, v222, v55, s[8:9]
	v_cndmask_b32_e64 v43, v223, v54, s[8:9]
	v_cndmask_b32_e64 v40, v224, v53, s[8:9]
	v_cndmask_b32_e64 v41, v225, v52, s[8:9]
.LBB0_684:
	s_or_b64 exec, exec, s[4:5]
	s_waitcnt vmcnt(6) lgkmcnt(1)
	v_add_f32_e32 v48, v201, v204
	v_fmamk_f32 v48, v48, 0x3a800000, v195
	v_rsq_f32_e32 v48, v48
	s_nop 0
	v_pk_mul_f32 v[30:31], v[30:31], v[48:49] op_sel_hi:[1,0]
	v_pk_mul_f32 v[28:29], v[28:29], v[48:49] op_sel_hi:[1,0]
	v_pk_mul_f32 v[50:51], v[26:27], v[48:49] op_sel_hi:[1,0]
	s_and_b64 vcc, exec, s[12:13]
	v_pk_mul_f32 v[52:53], v[24:25], v[48:49] op_sel_hi:[1,0]
	s_cbranch_vccnz .LBB0_686
	ds_bpermute_b32 v24, v198, v28
	ds_bpermute_b32 v25, v198, v29
	ds_bpermute_b32 v26, v198, v52
	ds_bpermute_b32 v54, v198, v30
	ds_bpermute_b32 v55, v198, v31
	ds_bpermute_b32 v27, v198, v53
	ds_bpermute_b32 v56, v198, v50
	ds_bpermute_b32 v57, v198, v51
	s_waitcnt lgkmcnt(6)
	v_pk_mul_f32 v[24:25], v[44:45], v[24:25]
	s_waitcnt lgkmcnt(3)
	v_pk_mul_f32 v[54:55], v[46:47], v[54:55]
	s_waitcnt vmcnt(5)
	v_pk_fma_f32 v[28:29], v[28:29], v[226:227], v[24:25]
	s_waitcnt lgkmcnt(2)
	v_pk_mul_f32 v[24:25], v[42:43], v[26:27]
	s_waitcnt lgkmcnt(0)
	v_pk_mul_f32 v[26:27], v[40:41], v[56:57]
	v_pk_fma_f32 v[30:31], v[30:31], v[228:229], v[54:55]
	s_waitcnt vmcnt(4)
	v_pk_fma_f32 v[50:51], v[50:51], v[232:233], v[26:27]
	v_pk_fma_f32 v[52:53], v[52:53], v[230:231], v[24:25]
.LBB0_686:
	v_lshlrev_b64 v[24:25], 11, v[158:159]
	v_mov_b32_e32 v26, v120
	v_mov_b32_e32 v27, v120
	v_pk_mul_f32 v[28:29], v[120:121], v[28:29]
	v_lshl_add_u64 v[24:25], v[122:123], 0, v[24:25]
	v_pk_mul_f32 v[30:31], v[26:27], v[30:31]
	v_cvt_pk_bf16_f32 v28, v28, v29
	v_mov_b32_e32 v49, v48
	v_cvt_pk_bf16_f32 v29, v30, v31
	v_pk_mul_f32 v[50:51], v[26:27], v[50:51]
	v_pk_mul_f32 v[52:53], v[120:121], v[52:53]
	v_pk_mul_f32 v[20:21], v[20:21], v[48:49]
	v_cvt_pk_bf16_f32 v30, v52, v53
	v_cvt_pk_bf16_f32 v31, v50, v51
	global_store_dwordx4 v[24:25], v[28:31], off
	s_and_b64 vcc, exec, s[12:13]
	v_pk_mul_f32 v[16:17], v[16:17], v[48:49]
	v_mov_b32_e32 v28, v48
	v_mov_b32_e32 v29, v48
	v_pk_mul_f32 v[22:23], v[22:23], v[28:29]
	v_pk_mul_f32 v[18:19], v[18:19], v[28:29]
	s_cbranch_vccnz .LBB0_688
	ds_bpermute_b32 v28, v198, v20
	ds_bpermute_b32 v29, v198, v21
	ds_bpermute_b32 v30, v198, v16
	ds_bpermute_b32 v48, v198, v22
	ds_bpermute_b32 v49, v198, v23
	ds_bpermute_b32 v31, v198, v17
	ds_bpermute_b32 v50, v198, v18
	ds_bpermute_b32 v51, v198, v19
	s_waitcnt lgkmcnt(6)
	v_pk_mul_f32 v[28:29], v[44:45], v[28:29]
	s_waitcnt lgkmcnt(3)
	v_pk_mul_f32 v[44:45], v[46:47], v[48:49]
	s_waitcnt vmcnt(6)
	v_pk_fma_f32 v[20:21], v[20:21], v[226:227], v[28:29]
	s_waitcnt lgkmcnt(2)
	v_pk_mul_f32 v[28:29], v[42:43], v[30:31]
	s_waitcnt lgkmcnt(0)
	v_pk_mul_f32 v[30:31], v[40:41], v[50:51]
	v_pk_fma_f32 v[22:23], v[22:23], v[228:229], v[44:45]
	s_waitcnt vmcnt(5)
	v_pk_fma_f32 v[18:19], v[18:19], v[232:233], v[30:31]
	v_pk_fma_f32 v[16:17], v[16:17], v[230:231], v[28:29]
.LBB0_688:
	v_pk_mul_f32 v[22:23], v[26:27], v[22:23]
	v_pk_mul_f32 v[26:27], v[26:27], v[18:19]
	v_pk_mul_f32 v[18:19], v[120:121], v[16:17]
	v_pk_mul_f32 v[20:21], v[120:121], v[20:21]
	v_mov_b32_e32 v28, 0
	v_cvt_pk_bf16_f32 v16, v20, v21
	v_cvt_pk_bf16_f32 v17, v22, v23
	v_cvt_pk_bf16_f32 v18, v18, v19
	v_cvt_pk_bf16_f32 v19, v26, v27
	global_store_dwordx4 v[24:25], v[16:19], off offset:256
	v_mov_b32_e32 v29, 0
	v_mov_b32_e32 v30, 0
	v_mov_b32_e32 v31, 0
	v_mov_b32_e32 v26, 0
	v_mov_b32_e32 v27, 0
	v_mov_b32_e32 v24, 0
	v_mov_b32_e32 v25, 0
	s_and_saveexec_b64 s[4:5], s[46:47]
	s_cbranch_execz .LBB0_690
	s_waitcnt vmcnt(3)
	v_xor_b32_e32 v31, 0x80000000, v237
	v_xor_b32_e32 v30, 0x80000000, v236
	v_xor_b32_e32 v29, 0x80000000, v235
	v_xor_b32_e32 v28, 0x80000000, v234
	s_waitcnt vmcnt(2)
	v_xor_b32_e32 v36, 0x80000000, v241
	v_xor_b32_e32 v37, 0x80000000, v240
	v_xor_b32_e32 v38, 0x80000000, v239
	v_xor_b32_e32 v39, 0x80000000, v238
	v_cndmask_b32_e64 v28, v234, v28, s[8:9]
	v_cndmask_b32_e64 v29, v235, v29, s[8:9]
	v_cndmask_b32_e64 v30, v236, v30, s[8:9]
	v_cndmask_b32_e64 v31, v237, v31, s[8:9]
	v_cndmask_b32_e64 v26, v238, v39, s[8:9]
	v_cndmask_b32_e64 v27, v239, v38, s[8:9]
	v_cndmask_b32_e64 v24, v240, v37, s[8:9]
	v_cndmask_b32_e64 v25, v241, v36, s[8:9]
.LBB0_690:
	s_or_b64 exec, exec, s[4:5]
	s_waitcnt vmcnt(2) lgkmcnt(0)
	v_add_f32_e32 v32, v199, v200
	v_fmamk_f32 v32, v32, 0x3a800000, v195
	v_rsq_f32_e32 v32, v32
	s_nop 0
	v_pk_mul_f32 v[14:15], v[14:15], v[32:33] op_sel_hi:[1,0]
	v_pk_mul_f32 v[12:13], v[12:13], v[32:33] op_sel_hi:[1,0]
	v_pk_mul_f32 v[34:35], v[10:11], v[32:33] op_sel_hi:[1,0]
	s_and_b64 vcc, exec, s[12:13]
	v_pk_mul_f32 v[36:37], v[8:9], v[32:33] op_sel_hi:[1,0]
	s_cbranch_vccnz .LBB0_692
	ds_bpermute_b32 v8, v198, v12
	ds_bpermute_b32 v9, v198, v13
	ds_bpermute_b32 v10, v198, v36
	ds_bpermute_b32 v38, v198, v14
	ds_bpermute_b32 v39, v198, v15
	ds_bpermute_b32 v11, v198, v37
	ds_bpermute_b32 v40, v198, v34
	ds_bpermute_b32 v41, v198, v35
	s_waitcnt lgkmcnt(6)
	v_pk_mul_f32 v[8:9], v[28:29], v[8:9]
	s_waitcnt lgkmcnt(3)
	v_pk_mul_f32 v[38:39], v[30:31], v[38:39]
	s_waitcnt vmcnt(1)
	v_pk_fma_f32 v[12:13], v[12:13], v[242:243], v[8:9]
	s_waitcnt lgkmcnt(2)
	v_pk_mul_f32 v[8:9], v[26:27], v[10:11]
	s_waitcnt lgkmcnt(0)
	v_pk_mul_f32 v[10:11], v[24:25], v[40:41]
	v_pk_fma_f32 v[14:15], v[14:15], v[244:245], v[38:39]
	s_waitcnt vmcnt(0)
	v_pk_fma_f32 v[34:35], v[34:35], v[248:249], v[10:11]
	v_pk_fma_f32 v[36:37], v[36:37], v[246:247], v[8:9]
.LBB0_692:
	v_lshlrev_b64 v[8:9], 11, v[156:157]
	v_mov_b32_e32 v10, v120
	v_mov_b32_e32 v11, v120
	v_pk_mul_f32 v[12:13], v[120:121], v[12:13]
	v_lshl_add_u64 v[8:9], v[122:123], 0, v[8:9]
	v_pk_mul_f32 v[14:15], v[10:11], v[14:15]
	v_cvt_pk_bf16_f32 v12, v12, v13
	v_mov_b32_e32 v33, v32
	v_cvt_pk_bf16_f32 v13, v14, v15
	v_pk_mul_f32 v[34:35], v[10:11], v[34:35]
	v_pk_mul_f32 v[36:37], v[120:121], v[36:37]
	v_pk_mul_f32 v[4:5], v[4:5], v[32:33]
	v_cvt_pk_bf16_f32 v14, v36, v37
	v_cvt_pk_bf16_f32 v15, v34, v35
	global_store_dwordx4 v[8:9], v[12:15], off
	s_and_b64 vcc, exec, s[12:13]
	v_pk_mul_f32 v[0:1], v[0:1], v[32:33]
	v_mov_b32_e32 v12, v32
	v_mov_b32_e32 v13, v32
	v_pk_mul_f32 v[6:7], v[6:7], v[12:13]
	v_pk_mul_f32 v[2:3], v[2:3], v[12:13]
	s_cbranch_vccnz .LBB0_694
	ds_bpermute_b32 v12, v198, v4
	ds_bpermute_b32 v13, v198, v5
	ds_bpermute_b32 v14, v198, v0
	ds_bpermute_b32 v32, v198, v6
	ds_bpermute_b32 v33, v198, v7
	ds_bpermute_b32 v15, v198, v1
	ds_bpermute_b32 v34, v198, v2
	ds_bpermute_b32 v35, v198, v3
	s_waitcnt lgkmcnt(6)
	v_pk_mul_f32 v[12:13], v[28:29], v[12:13]
	s_waitcnt lgkmcnt(3)
	v_pk_mul_f32 v[28:29], v[30:31], v[32:33]
	s_waitcnt vmcnt(2)
	v_pk_fma_f32 v[4:5], v[4:5], v[242:243], v[12:13]
	s_waitcnt lgkmcnt(2)
	v_pk_mul_f32 v[12:13], v[26:27], v[14:15]
	s_waitcnt lgkmcnt(0)
	v_pk_mul_f32 v[14:15], v[24:25], v[34:35]
	v_pk_fma_f32 v[6:7], v[6:7], v[244:245], v[28:29]
	s_waitcnt vmcnt(1)
	v_pk_fma_f32 v[2:3], v[2:3], v[248:249], v[14:15]
	v_pk_fma_f32 v[0:1], v[0:1], v[246:247], v[12:13]
